# FFN-up epilogue: conv weight/bias loads issued before the accumulator staging instead of after its barrier
# baseline (speedup 1.0000x reference)
.LBB0_640:
	s_and_b64 s[2:3], s[8:9], exec
	s_waitcnt vmcnt(0)
	v_readlane_b32 s2, v255, 15
	v_readlane_b32 s4, v255, 19
	v_readlane_b32 s3, v255, 16
	v_readlane_b32 s5, v255, 20
	s_cselect_b32 s42, s2, s4
	v_readlane_b32 s2, v255, 17
	s_cselect_b32 s28, s51, 0
	s_cselect_b32 s29, s52, 0
	s_cselect_b32 s43, s3, s5
	s_cselect_b32 s46, s2, 0
	s_cmp_lt_i32 s44, 4
	s_mov_b64 s[2:3], -1
	s_waitcnt vmcnt(0) lgkmcnt(0)
	s_barrier
	s_cbranch_scc1 .LBB0_1047
	s_cmp_lt_i32 s44, 6
	s_cbranch_scc1 .LBB0_1041
	s_cmp_gt_i32 s44, 6
	s_cbranch_scc0 .LBB0_654
	v_lshlrev_b32_e32 v245, 2, v175
	v_and_b32_e32 v245, 0x7c, v245
	s_mul_i32 s2, s28, 0x10800
	v_readlane_b32 s48, v253, 61
	v_lshl_or_b32 v164, s47, 7, v245
	s_mul_hi_u32 s3, s28, 0x10800
	v_readlane_b32 s49, v253, 62
	s_add_u32 s2, s48, s2
	v_ashrrev_i32_e32 v165, 31, v164
	s_addc_u32 s3, s49, s3
	v_lshlrev_b64 v[130:131], 2, v[164:165]
	v_lshl_add_u64 v[150:151], s[2:3], 0, v[130:131]
	s_movk_i32 s2, 0x5000
	v_add_co_u32_e32 v134, vcc, s2, v150
	s_mov_b32 s2, 0xb000
	s_nop 0
	v_addc_co_u32_e32 v135, vcc, 0, v151, vcc
	v_add_co_u32_e32 v138, vcc, s2, v150
	v_readlane_b32 s50, v253, 63
	s_nop 0
	v_addc_co_u32_e32 v139, vcc, 0, v151, vcc
	v_add_co_u32_e32 v142, vcc, s25, v150
	s_mul_i32 s4, s28, 0x5800
	s_nop 0
	v_addc_co_u32_e32 v143, vcc, 0, v151, vcc
	s_mov_b32 s2, 0x8000
	v_readlane_b32 s51, v254, 0
	s_mul_hi_u32 s5, s28, 0x5800
	s_add_u32 s4, s50, s4
	v_add_co_u32_e32 v146, vcc, s2, v150
	s_addc_u32 s5, s51, s5
	s_nop 0
	v_addc_co_u32_e32 v147, vcc, 0, v151, vcc
	s_mov_b32 s2, 0xd000
	v_lshl_add_u64 v[158:159], s[4:5], 0, v[130:131]
	global_load_dwordx4 v[130:133], v[150:151], off
	v_add_co_u32_e32 v150, vcc, s2, v150
	global_load_dwordx4 v[134:137], v[134:135], off offset:2048
	s_nop 0
	global_load_dwordx4 v[138:141], v[138:139], off
	v_addc_co_u32_e32 v151, vcc, 0, v151, vcc
	global_load_dwordx4 v[142:145], v[142:143], off offset:3072
	s_nop 0
	global_load_dwordx4 v[146:149], v[146:147], off offset:1024
	s_nop 0
	global_load_dwordx4 v[150:153], v[150:151], off offset:3072
	s_nop 0
	global_load_dwordx4 v[154:157], v[158:159], off
	v_add_co_u32_e32 v158, vcc, 0x2000, v158
	s_nop 0
	v_addc_co_u32_e32 v159, vcc, 0, v159, vcc
	global_load_dwordx4 v[158:161], v[158:159], off offset:3072
	s_movk_i32 s15, 0x210
	v_lshlrev_b32_e32 v0, 3, v223
	v_mul_lo_u32 v242, v225, s15
	v_cvt_pk_bf16_f32 v241, v128, v129
	v_cvt_pk_bf16_f32 v240, v126, v127
	v_add3_u32 v0, v224, v242, v0
	v_cvt_pk_bf16_f32 v243, v124, v125
	v_cvt_pk_bf16_f32 v242, v122, v123
	ds_write2_b64 v0, v[240:241], v[242:243] offset1:4
	v_cvt_pk_bf16_f32 v241, v120, v121
	v_cvt_pk_bf16_f32 v240, v118, v119
	v_cvt_pk_bf16_f32 v243, v116, v117
	v_cvt_pk_bf16_f32 v242, v114, v115
	ds_write2_b64 v0, v[240:241], v[242:243] offset0:32 offset1:36
	v_cvt_pk_bf16_f32 v241, v112, v113
	v_cvt_pk_bf16_f32 v240, v110, v111
	v_cvt_pk_bf16_f32 v243, v108, v109
	v_cvt_pk_bf16_f32 v242, v106, v107
	v_add_u32_e32 v244, 0x2000, v0
	ds_write2_b64 v244, v[240:241], v[242:243] offset0:32 offset1:36
	v_cvt_pk_bf16_f32 v241, v104, v105
	v_cvt_pk_bf16_f32 v240, v102, v103
	v_cvt_pk_bf16_f32 v243, v100, v101
	v_cvt_pk_bf16_f32 v242, v98, v99
	ds_write2_b64 v244, v[240:241], v[242:243] offset0:64 offset1:68
	v_cvt_pk_bf16_f32 v241, v96, v97
	v_cvt_pk_bf16_f32 v240, v94, v95
	v_cvt_pk_bf16_f32 v243, v92, v93
	v_cvt_pk_bf16_f32 v242, v90, v91
	v_add_u32_e32 v244, 0x4000, v0
	ds_write2_b64 v244, v[240:241], v[242:243] offset0:64 offset1:68
	v_cvt_pk_bf16_f32 v241, v88, v89
	v_cvt_pk_bf16_f32 v240, v86, v87
	v_cvt_pk_bf16_f32 v243, v84, v85
	v_cvt_pk_bf16_f32 v242, v82, v83
	ds_write2_b64 v244, v[240:241], v[242:243] offset0:96 offset1:100
	v_cvt_pk_bf16_f32 v241, v80, v81
	v_cvt_pk_bf16_f32 v240, v78, v79
	v_cvt_pk_bf16_f32 v243, v76, v77
	v_cvt_pk_bf16_f32 v242, v74, v75
	v_add_u32_e32 v244, 0x6000, v0
	ds_write2_b64 v244, v[240:241], v[242:243] offset0:96 offset1:100
	v_cvt_pk_bf16_f32 v241, v72, v73
	v_cvt_pk_bf16_f32 v240, v70, v71
	v_cvt_pk_bf16_f32 v243, v68, v69
	v_cvt_pk_bf16_f32 v242, v66, v67
	ds_write2_b64 v244, v[240:241], v[242:243] offset0:128 offset1:132
	v_cvt_pk_bf16_f32 v241, v64, v65
	v_cvt_pk_bf16_f32 v240, v62, v63
	v_cvt_pk_bf16_f32 v243, v60, v61
	v_cvt_pk_bf16_f32 v242, v58, v59
	v_add_u32_e32 v244, 0x8000, v0
	ds_write2_b64 v244, v[240:241], v[242:243] offset0:128 offset1:132
	v_cvt_pk_bf16_f32 v241, v56, v57
	v_cvt_pk_bf16_f32 v240, v54, v55
	v_cvt_pk_bf16_f32 v243, v52, v53
	v_cvt_pk_bf16_f32 v242, v50, v51
	ds_write2_b64 v244, v[240:241], v[242:243] offset0:160 offset1:164
	v_cvt_pk_bf16_f32 v241, v48, v49
	v_cvt_pk_bf16_f32 v240, v46, v47
	v_cvt_pk_bf16_f32 v243, v44, v45
	v_cvt_pk_bf16_f32 v242, v42, v43
	v_add_u32_e32 v244, 0xa000, v0
	ds_write2_b64 v244, v[240:241], v[242:243] offset0:160 offset1:164
	v_cvt_pk_bf16_f32 v241, v36, v37
	v_cvt_pk_bf16_f32 v240, v34, v35
	v_cvt_pk_bf16_f32 v243, v32, v33
	v_cvt_pk_bf16_f32 v242, v30, v31
	ds_write2_b64 v244, v[240:241], v[242:243] offset0:192 offset1:196
	v_cvt_pk_bf16_f32 v241, v40, v41
	v_cvt_pk_bf16_f32 v240, v38, v39
	v_cvt_pk_bf16_f32 v243, v28, v29
	v_cvt_pk_bf16_f32 v242, v26, v27
	v_add_u32_e32 v244, 0xc000, v0
	ds_write2_b64 v244, v[240:241], v[242:243] offset0:192 offset1:196
	v_cvt_pk_bf16_f32 v241, v24, v25
	v_cvt_pk_bf16_f32 v240, v22, v23
	v_cvt_pk_bf16_f32 v243, v20, v21
	v_cvt_pk_bf16_f32 v242, v18, v19
	ds_write2_b64 v244, v[240:241], v[242:243] offset0:224 offset1:228
	v_cvt_pk_bf16_f32 v241, v16, v17
	v_cvt_pk_bf16_f32 v240, v14, v15
	v_cvt_pk_bf16_f32 v243, v12, v13
	v_cvt_pk_bf16_f32 v242, v10, v11
	v_add_u32_e32 v244, 0xe000, v0
	ds_write2_b64 v244, v[240:241], v[242:243] offset0:224 offset1:228
	v_cvt_pk_bf16_f32 v241, v8, v9
	v_cvt_pk_bf16_f32 v240, v6, v7
	v_cvt_pk_bf16_f32 v243, v4, v5
	v_cvt_pk_bf16_f32 v242, v2, v3
	v_add_u32_e32 v0, 0xe800, v0
	ds_write2_b64 v0, v[240:241], v[242:243] offset1:4
	s_waitcnt lgkmcnt(0)
	s_barrier
	v_ashrrev_i32_e32 v0, 5, v175
	v_readlane_b32 s2, v252, 32
	v_readlane_b32 s3, v252, 33
	v_mul_lo_u32 v166, v0, s15
	v_and_b32_e32 v167, 31, v175
	s_mov_b32 s14, 0
	v_lshl_add_u64 v[164:165], v[164:165], 1, s[2:3]
	v_lshl_add_u32 v166, v167, 3, v166
	v_add_u32_e32 v167, s40, v0
	s_waitcnt vmcnt(0)
	s_mov_b32 s14, 0x8800
	v_mul_u32_u24_e32 v63, 0x2100, v0
	v_and_b32_e32 v64, 31, v175
	v_lshl_add_u32 v63, v64, 3, v63
	v_lshlrev_b32_e32 v61, 4, v0
	v_add_u32_e32 v61, 1, v61
	v_add_u32_e32 v62, s40, v61
	s_mov_b32 s4, 0x78787879
	v_mul_hi_i32 v60, v62, s4
	v_lshrrev_b32_e32 v64, 31, v60
	v_ashrrev_i32_e32 v60, 11, v60
	v_add_u32_e32 v60, v60, v64
	v_mul_i32_i24_e32 v60, 0x1100, v60
	v_sub_u32_e32 v60, v62, v60
	s_movk_i32 s4, 0x1600
	v_mad_i64_i32 v[58:59], s[4:5], v62, s4, v[164:165]
	v_mov_b32_e32 v56, 0x1600
	v_mov_b32_e32 v57, 0
	ds_read2_b64 v[26:29], v63 offset1:32
	ds_read2_b64 v[68:71], v63 offset0:66 offset1:98
	s_waitcnt lgkmcnt(0)
	v_lshlrev_b32_e32 v2, 16, v26
	v_and_b32_e32 v3, 0xffff0000, v26
	v_lshlrev_b32_e32 v4, 16, v27
	v_and_b32_e32 v5, 0xffff0000, v27
	v_lshlrev_b32_e32 v14, 16, v28
	v_and_b32_e32 v15, 0xffff0000, v28
	v_lshlrev_b32_e32 v16, 16, v29
	v_and_b32_e32 v17, 0xffff0000, v29
	v_lshlrev_b32_e32 v6, 16, v68
	v_and_b32_e32 v7, 0xffff0000, v68
	v_lshlrev_b32_e32 v8, 16, v69
	v_and_b32_e32 v9, 0xffff0000, v69
	v_lshlrev_b32_e32 v18, 16, v70
	v_and_b32_e32 v19, 0xffff0000, v70
	v_lshlrev_b32_e32 v20, 16, v71
	v_and_b32_e32 v21, 0xffff0000, v71
	v_add_u32_e32 v63, 0x420, v63
	v_add_u32_e32 v64, -1, v60
	v_add_u32_e32 v65, 0xfffffeff, v60
	v_cmp_gt_u32_e32 vcc, 0xfef, v65
	s_mov_b64 s[4:5], vcc
	v_cmp_gt_u32_e32 vcc, 0xef, v64
	s_or_b64 s[4:5], s[4:5], vcc
	v_add_u32_e32 v64, 15, v62
	v_cmp_gt_i32_e32 vcc, s14, v64
	s_and_b64 s[4:5], s[4:5], vcc
	s_xor_b64 s[4:5], s[4:5], exec
	s_cmp_eq_u64 s[4:5], 0
	s_cbranch_scc0 .Lconv_slow
	v_cmp_gt_u32_e32 vcc, 15, v0
	ds_read2_b64 v[26:29], v63 offset1:32
	s_waitcnt lgkmcnt(0)
	v_lshlrev_b32_e32 v10, 16, v26
	v_and_b32_e32 v11, 0xffff0000, v26
	v_lshlrev_b32_e32 v12, 16, v27
	v_and_b32_e32 v13, 0xffff0000, v27
	v_lshlrev_b32_e32 v22, 16, v28
	v_and_b32_e32 v23, 0xffff0000, v28
	v_lshlrev_b32_e32 v24, 16, v29
	v_and_b32_e32 v25, 0xffff0000, v29
	v_add_u32_e32 v63, 0x210, v63
	ds_read2_b64 v[26:29], v63 offset1:32
	v_pk_fma_f32 v[30:31], v[146:147], v[18:19], v[158:159]
	v_pk_fma_f32 v[32:33], v[148:149], v[20:21], v[160:161]
	v_pk_fma_f32 v[34:35], v[134:135], v[6:7], v[154:155]
	v_pk_fma_f32 v[36:37], v[136:137], v[8:9], v[156:157]
	v_pk_fma_f32 v[30:31], v[142:143], v[14:15], v[30:31]
	v_pk_fma_f32 v[32:33], v[144:145], v[16:17], v[32:33]
	v_pk_fma_f32 v[34:35], v[130:131], v[2:3], v[34:35]
	v_pk_fma_f32 v[36:37], v[132:133], v[4:5], v[36:37]
	v_pk_fma_f32 v[30:31], v[150:151], v[22:23], v[30:31]
	v_pk_fma_f32 v[32:33], v[152:153], v[24:25], v[32:33]
	v_pk_fma_f32 v[34:35], v[138:139], v[10:11], v[34:35]
	v_pk_fma_f32 v[36:37], v[140:141], v[12:13], v[36:37]
	v_mul_f32_e32 v42, 0xbfb8aa3b, v30
	v_mul_f32_e32 v43, 0xbfb8aa3b, v31
	v_mul_f32_e32 v44, 0xbfb8aa3b, v32
	v_mul_f32_e32 v45, 0xbfb8aa3b, v33
	v_exp_f32_e32 v42, v42
	v_exp_f32_e32 v43, v43
	v_exp_f32_e32 v44, v44
	v_exp_f32_e32 v45, v45
	v_pk_add_f32 v[42:43], v[42:43], 1.0 op_sel_hi:[1,0]
	v_pk_add_f32 v[44:45], v[44:45], 1.0 op_sel_hi:[1,0]
	v_rcp_f32_e32 v46, v42
	v_rcp_f32_e32 v47, v43
	v_rcp_f32_e32 v48, v44
	v_rcp_f32_e32 v49, v45
	v_mul_f32_e32 v46, v30, v46
	v_mul_f32_e32 v47, v31, v47
	v_mul_f32_e32 v48, v32, v48
	v_mul_f32_e32 v49, v33, v49
	v_pk_mul_f32 v[34:35], v[34:35], v[46:47]
	v_pk_mul_f32 v[36:37], v[36:37], v[48:49]
	v_cvt_pk_bf16_f32 v66, v34, v35
	v_cvt_pk_bf16_f32 v67, v36, v37
	global_store_dwordx2 v[58:59], v[66:67], off
	v_lshl_add_u64 v[58:59], v[58:59], 0, v[56:57]
	s_waitcnt lgkmcnt(0)
	v_lshlrev_b32_e32 v2, 16, v26
	v_and_b32_e32 v3, 0xffff0000, v26
	v_lshlrev_b32_e32 v4, 16, v27
	v_and_b32_e32 v5, 0xffff0000, v27
	v_lshlrev_b32_e32 v14, 16, v28
	v_and_b32_e32 v15, 0xffff0000, v28
	v_lshlrev_b32_e32 v16, 16, v29
	v_and_b32_e32 v17, 0xffff0000, v29
	v_add_u32_e32 v63, 0x210, v63
	ds_read2_b64 v[26:29], v63 offset1:32
	v_pk_fma_f32 v[30:31], v[146:147], v[22:23], v[158:159]
	v_pk_fma_f32 v[32:33], v[148:149], v[24:25], v[160:161]
	v_pk_fma_f32 v[34:35], v[134:135], v[10:11], v[154:155]
	v_pk_fma_f32 v[36:37], v[136:137], v[12:13], v[156:157]
	v_pk_fma_f32 v[30:31], v[142:143], v[18:19], v[30:31]
	v_pk_fma_f32 v[32:33], v[144:145], v[20:21], v[32:33]
	v_pk_fma_f32 v[34:35], v[130:131], v[6:7], v[34:35]
	v_pk_fma_f32 v[36:37], v[132:133], v[8:9], v[36:37]
	v_pk_fma_f32 v[30:31], v[150:151], v[14:15], v[30:31]
	v_pk_fma_f32 v[32:33], v[152:153], v[16:17], v[32:33]
	v_pk_fma_f32 v[34:35], v[138:139], v[2:3], v[34:35]
	v_pk_fma_f32 v[36:37], v[140:141], v[4:5], v[36:37]
	v_mul_f32_e32 v42, 0xbfb8aa3b, v30
	v_mul_f32_e32 v43, 0xbfb8aa3b, v31
	v_mul_f32_e32 v44, 0xbfb8aa3b, v32
	v_mul_f32_e32 v45, 0xbfb8aa3b, v33
	v_exp_f32_e32 v42, v42
	v_exp_f32_e32 v43, v43
	v_exp_f32_e32 v44, v44
	v_exp_f32_e32 v45, v45
	v_pk_add_f32 v[42:43], v[42:43], 1.0 op_sel_hi:[1,0]
	v_pk_add_f32 v[44:45], v[44:45], 1.0 op_sel_hi:[1,0]
	v_rcp_f32_e32 v46, v42
	v_rcp_f32_e32 v47, v43
	v_rcp_f32_e32 v48, v44
	v_rcp_f32_e32 v49, v45
	v_mul_f32_e32 v46, v30, v46
	v_mul_f32_e32 v47, v31, v47
	v_mul_f32_e32 v48, v32, v48
	v_mul_f32_e32 v49, v33, v49
	v_pk_mul_f32 v[34:35], v[34:35], v[46:47]
	v_pk_mul_f32 v[36:37], v[36:37], v[48:49]
	v_cvt_pk_bf16_f32 v66, v34, v35
	v_cvt_pk_bf16_f32 v67, v36, v37
	global_store_dwordx2 v[58:59], v[66:67], off
	v_lshl_add_u64 v[58:59], v[58:59], 0, v[56:57]
	s_waitcnt lgkmcnt(0)
	v_lshlrev_b32_e32 v6, 16, v26
	v_and_b32_e32 v7, 0xffff0000, v26
	v_lshlrev_b32_e32 v8, 16, v27
	v_and_b32_e32 v9, 0xffff0000, v27
	v_lshlrev_b32_e32 v18, 16, v28
	v_and_b32_e32 v19, 0xffff0000, v28
	v_lshlrev_b32_e32 v20, 16, v29
	v_and_b32_e32 v21, 0xffff0000, v29
	v_add_u32_e32 v63, 0x210, v63
	ds_read2_b64 v[26:29], v63 offset1:32
	v_pk_fma_f32 v[30:31], v[146:147], v[14:15], v[158:159]
	v_pk_fma_f32 v[32:33], v[148:149], v[16:17], v[160:161]
	v_pk_fma_f32 v[34:35], v[134:135], v[2:3], v[154:155]
	v_pk_fma_f32 v[36:37], v[136:137], v[4:5], v[156:157]
	v_pk_fma_f32 v[30:31], v[142:143], v[22:23], v[30:31]
	v_pk_fma_f32 v[32:33], v[144:145], v[24:25], v[32:33]
	v_pk_fma_f32 v[34:35], v[130:131], v[10:11], v[34:35]
	v_pk_fma_f32 v[36:37], v[132:133], v[12:13], v[36:37]
	v_pk_fma_f32 v[30:31], v[150:151], v[18:19], v[30:31]
	v_pk_fma_f32 v[32:33], v[152:153], v[20:21], v[32:33]
	v_pk_fma_f32 v[34:35], v[138:139], v[6:7], v[34:35]
	v_pk_fma_f32 v[36:37], v[140:141], v[8:9], v[36:37]
	v_mul_f32_e32 v42, 0xbfb8aa3b, v30
	v_mul_f32_e32 v43, 0xbfb8aa3b, v31
	v_mul_f32_e32 v44, 0xbfb8aa3b, v32
	v_mul_f32_e32 v45, 0xbfb8aa3b, v33
	v_exp_f32_e32 v42, v42
	v_exp_f32_e32 v43, v43
	v_exp_f32_e32 v44, v44
	v_exp_f32_e32 v45, v45
	v_pk_add_f32 v[42:43], v[42:43], 1.0 op_sel_hi:[1,0]
	v_pk_add_f32 v[44:45], v[44:45], 1.0 op_sel_hi:[1,0]
	v_rcp_f32_e32 v46, v42
	v_rcp_f32_e32 v47, v43
	v_rcp_f32_e32 v48, v44
	v_rcp_f32_e32 v49, v45
	v_mul_f32_e32 v46, v30, v46
	v_mul_f32_e32 v47, v31, v47
	v_mul_f32_e32 v48, v32, v48
	v_mul_f32_e32 v49, v33, v49
	v_pk_mul_f32 v[34:35], v[34:35], v[46:47]
	v_pk_mul_f32 v[36:37], v[36:37], v[48:49]
	v_cvt_pk_bf16_f32 v66, v34, v35
	v_cvt_pk_bf16_f32 v67, v36, v37
	global_store_dwordx2 v[58:59], v[66:67], off
	v_lshl_add_u64 v[58:59], v[58:59], 0, v[56:57]
	s_waitcnt lgkmcnt(0)
	v_lshlrev_b32_e32 v10, 16, v26
	v_and_b32_e32 v11, 0xffff0000, v26
	v_lshlrev_b32_e32 v12, 16, v27
	v_and_b32_e32 v13, 0xffff0000, v27
	v_lshlrev_b32_e32 v22, 16, v28
	v_and_b32_e32 v23, 0xffff0000, v28
	v_lshlrev_b32_e32 v24, 16, v29
	v_and_b32_e32 v25, 0xffff0000, v29
	v_add_u32_e32 v63, 0x210, v63
	ds_read2_b64 v[26:29], v63 offset1:32
	v_pk_fma_f32 v[30:31], v[146:147], v[18:19], v[158:159]
	v_pk_fma_f32 v[32:33], v[148:149], v[20:21], v[160:161]
	v_pk_fma_f32 v[34:35], v[134:135], v[6:7], v[154:155]
	v_pk_fma_f32 v[36:37], v[136:137], v[8:9], v[156:157]
	v_pk_fma_f32 v[30:31], v[142:143], v[14:15], v[30:31]
	v_pk_fma_f32 v[32:33], v[144:145], v[16:17], v[32:33]
	v_pk_fma_f32 v[34:35], v[130:131], v[2:3], v[34:35]
	v_pk_fma_f32 v[36:37], v[132:133], v[4:5], v[36:37]
	v_pk_fma_f32 v[30:31], v[150:151], v[22:23], v[30:31]
	v_pk_fma_f32 v[32:33], v[152:153], v[24:25], v[32:33]
	v_pk_fma_f32 v[34:35], v[138:139], v[10:11], v[34:35]
	v_pk_fma_f32 v[36:37], v[140:141], v[12:13], v[36:37]
	v_mul_f32_e32 v42, 0xbfb8aa3b, v30
	v_mul_f32_e32 v43, 0xbfb8aa3b, v31
	v_mul_f32_e32 v44, 0xbfb8aa3b, v32
	v_mul_f32_e32 v45, 0xbfb8aa3b, v33
	v_exp_f32_e32 v42, v42
	v_exp_f32_e32 v43, v43
	v_exp_f32_e32 v44, v44
	v_exp_f32_e32 v45, v45
	v_pk_add_f32 v[42:43], v[42:43], 1.0 op_sel_hi:[1,0]
	v_pk_add_f32 v[44:45], v[44:45], 1.0 op_sel_hi:[1,0]
	v_rcp_f32_e32 v46, v42
	v_rcp_f32_e32 v47, v43
	v_rcp_f32_e32 v48, v44
	v_rcp_f32_e32 v49, v45
	v_mul_f32_e32 v46, v30, v46
	v_mul_f32_e32 v47, v31, v47
	v_mul_f32_e32 v48, v32, v48
	v_mul_f32_e32 v49, v33, v49
	v_pk_mul_f32 v[34:35], v[34:35], v[46:47]
	v_pk_mul_f32 v[36:37], v[36:37], v[48:49]
	v_cvt_pk_bf16_f32 v66, v34, v35
	v_cvt_pk_bf16_f32 v67, v36, v37
	global_store_dwordx2 v[58:59], v[66:67], off
	v_lshl_add_u64 v[58:59], v[58:59], 0, v[56:57]
	s_waitcnt lgkmcnt(0)
	v_lshlrev_b32_e32 v2, 16, v26
	v_and_b32_e32 v3, 0xffff0000, v26
	v_lshlrev_b32_e32 v4, 16, v27
	v_and_b32_e32 v5, 0xffff0000, v27
	v_lshlrev_b32_e32 v14, 16, v28
	v_and_b32_e32 v15, 0xffff0000, v28
	v_lshlrev_b32_e32 v16, 16, v29
	v_and_b32_e32 v17, 0xffff0000, v29
	v_add_u32_e32 v63, 0x210, v63
	ds_read2_b64 v[26:29], v63 offset1:32
	v_pk_fma_f32 v[30:31], v[146:147], v[22:23], v[158:159]
	v_pk_fma_f32 v[32:33], v[148:149], v[24:25], v[160:161]
	v_pk_fma_f32 v[34:35], v[134:135], v[10:11], v[154:155]
	v_pk_fma_f32 v[36:37], v[136:137], v[12:13], v[156:157]
	v_pk_fma_f32 v[30:31], v[142:143], v[18:19], v[30:31]
	v_pk_fma_f32 v[32:33], v[144:145], v[20:21], v[32:33]
	v_pk_fma_f32 v[34:35], v[130:131], v[6:7], v[34:35]
	v_pk_fma_f32 v[36:37], v[132:133], v[8:9], v[36:37]
	v_pk_fma_f32 v[30:31], v[150:151], v[14:15], v[30:31]
	v_pk_fma_f32 v[32:33], v[152:153], v[16:17], v[32:33]
	v_pk_fma_f32 v[34:35], v[138:139], v[2:3], v[34:35]
	v_pk_fma_f32 v[36:37], v[140:141], v[4:5], v[36:37]
	v_mul_f32_e32 v42, 0xbfb8aa3b, v30
	v_mul_f32_e32 v43, 0xbfb8aa3b, v31
	v_mul_f32_e32 v44, 0xbfb8aa3b, v32
	v_mul_f32_e32 v45, 0xbfb8aa3b, v33
	v_exp_f32_e32 v42, v42
	v_exp_f32_e32 v43, v43
	v_exp_f32_e32 v44, v44
	v_exp_f32_e32 v45, v45
	v_pk_add_f32 v[42:43], v[42:43], 1.0 op_sel_hi:[1,0]
	v_pk_add_f32 v[44:45], v[44:45], 1.0 op_sel_hi:[1,0]
	v_rcp_f32_e32 v46, v42
	v_rcp_f32_e32 v47, v43
	v_rcp_f32_e32 v48, v44
	v_rcp_f32_e32 v49, v45
	v_mul_f32_e32 v46, v30, v46
	v_mul_f32_e32 v47, v31, v47
	v_mul_f32_e32 v48, v32, v48
	v_mul_f32_e32 v49, v33, v49
	v_pk_mul_f32 v[34:35], v[34:35], v[46:47]
	v_pk_mul_f32 v[36:37], v[36:37], v[48:49]
	v_cvt_pk_bf16_f32 v66, v34, v35
	v_cvt_pk_bf16_f32 v67, v36, v37
	global_store_dwordx2 v[58:59], v[66:67], off
	v_lshl_add_u64 v[58:59], v[58:59], 0, v[56:57]
	s_waitcnt lgkmcnt(0)
	v_lshlrev_b32_e32 v6, 16, v26
	v_and_b32_e32 v7, 0xffff0000, v26
	v_lshlrev_b32_e32 v8, 16, v27
	v_and_b32_e32 v9, 0xffff0000, v27
	v_lshlrev_b32_e32 v18, 16, v28
	v_and_b32_e32 v19, 0xffff0000, v28
	v_lshlrev_b32_e32 v20, 16, v29
	v_and_b32_e32 v21, 0xffff0000, v29
	v_add_u32_e32 v63, 0x210, v63
	ds_read2_b64 v[26:29], v63 offset1:32
	v_pk_fma_f32 v[30:31], v[146:147], v[14:15], v[158:159]
	v_pk_fma_f32 v[32:33], v[148:149], v[16:17], v[160:161]
	v_pk_fma_f32 v[34:35], v[134:135], v[2:3], v[154:155]
	v_pk_fma_f32 v[36:37], v[136:137], v[4:5], v[156:157]
	v_pk_fma_f32 v[30:31], v[142:143], v[22:23], v[30:31]
	v_pk_fma_f32 v[32:33], v[144:145], v[24:25], v[32:33]
	v_pk_fma_f32 v[34:35], v[130:131], v[10:11], v[34:35]
	v_pk_fma_f32 v[36:37], v[132:133], v[12:13], v[36:37]
	v_pk_fma_f32 v[30:31], v[150:151], v[18:19], v[30:31]
	v_pk_fma_f32 v[32:33], v[152:153], v[20:21], v[32:33]
	v_pk_fma_f32 v[34:35], v[138:139], v[6:7], v[34:35]
	v_pk_fma_f32 v[36:37], v[140:141], v[8:9], v[36:37]
	v_mul_f32_e32 v42, 0xbfb8aa3b, v30
	v_mul_f32_e32 v43, 0xbfb8aa3b, v31
	v_mul_f32_e32 v44, 0xbfb8aa3b, v32
	v_mul_f32_e32 v45, 0xbfb8aa3b, v33
	v_exp_f32_e32 v42, v42
	v_exp_f32_e32 v43, v43
	v_exp_f32_e32 v44, v44
	v_exp_f32_e32 v45, v45
	v_pk_add_f32 v[42:43], v[42:43], 1.0 op_sel_hi:[1,0]
	v_pk_add_f32 v[44:45], v[44:45], 1.0 op_sel_hi:[1,0]
	v_rcp_f32_e32 v46, v42
	v_rcp_f32_e32 v47, v43
	v_rcp_f32_e32 v48, v44
	v_rcp_f32_e32 v49, v45
	v_mul_f32_e32 v46, v30, v46
	v_mul_f32_e32 v47, v31, v47
	v_mul_f32_e32 v48, v32, v48
	v_mul_f32_e32 v49, v33, v49
	v_pk_mul_f32 v[34:35], v[34:35], v[46:47]
	v_pk_mul_f32 v[36:37], v[36:37], v[48:49]
	v_cvt_pk_bf16_f32 v66, v34, v35
	v_cvt_pk_bf16_f32 v67, v36, v37
	global_store_dwordx2 v[58:59], v[66:67], off
	v_lshl_add_u64 v[58:59], v[58:59], 0, v[56:57]
	s_waitcnt lgkmcnt(0)
	v_lshlrev_b32_e32 v10, 16, v26
	v_and_b32_e32 v11, 0xffff0000, v26
	v_lshlrev_b32_e32 v12, 16, v27
	v_and_b32_e32 v13, 0xffff0000, v27
	v_lshlrev_b32_e32 v22, 16, v28
	v_and_b32_e32 v23, 0xffff0000, v28
	v_lshlrev_b32_e32 v24, 16, v29
	v_and_b32_e32 v25, 0xffff0000, v29
	v_add_u32_e32 v63, 0x210, v63
	ds_read2_b64 v[26:29], v63 offset1:32
	v_pk_fma_f32 v[30:31], v[146:147], v[18:19], v[158:159]
	v_pk_fma_f32 v[32:33], v[148:149], v[20:21], v[160:161]
	v_pk_fma_f32 v[34:35], v[134:135], v[6:7], v[154:155]
	v_pk_fma_f32 v[36:37], v[136:137], v[8:9], v[156:157]
	v_pk_fma_f32 v[30:31], v[142:143], v[14:15], v[30:31]
	v_pk_fma_f32 v[32:33], v[144:145], v[16:17], v[32:33]
	v_pk_fma_f32 v[34:35], v[130:131], v[2:3], v[34:35]
	v_pk_fma_f32 v[36:37], v[132:133], v[4:5], v[36:37]
	v_pk_fma_f32 v[30:31], v[150:151], v[22:23], v[30:31]
	v_pk_fma_f32 v[32:33], v[152:153], v[24:25], v[32:33]
	v_pk_fma_f32 v[34:35], v[138:139], v[10:11], v[34:35]
	v_pk_fma_f32 v[36:37], v[140:141], v[12:13], v[36:37]
	v_mul_f32_e32 v42, 0xbfb8aa3b, v30
	v_mul_f32_e32 v43, 0xbfb8aa3b, v31
	v_mul_f32_e32 v44, 0xbfb8aa3b, v32
	v_mul_f32_e32 v45, 0xbfb8aa3b, v33
	v_exp_f32_e32 v42, v42
	v_exp_f32_e32 v43, v43
	v_exp_f32_e32 v44, v44
	v_exp_f32_e32 v45, v45
	v_pk_add_f32 v[42:43], v[42:43], 1.0 op_sel_hi:[1,0]
	v_pk_add_f32 v[44:45], v[44:45], 1.0 op_sel_hi:[1,0]
	v_rcp_f32_e32 v46, v42
	v_rcp_f32_e32 v47, v43
	v_rcp_f32_e32 v48, v44
	v_rcp_f32_e32 v49, v45
	v_mul_f32_e32 v46, v30, v46
	v_mul_f32_e32 v47, v31, v47
	v_mul_f32_e32 v48, v32, v48
	v_mul_f32_e32 v49, v33, v49
	v_pk_mul_f32 v[34:35], v[34:35], v[46:47]
	v_pk_mul_f32 v[36:37], v[36:37], v[48:49]
	v_cvt_pk_bf16_f32 v66, v34, v35
	v_cvt_pk_bf16_f32 v67, v36, v37
	global_store_dwordx2 v[58:59], v[66:67], off
	v_lshl_add_u64 v[58:59], v[58:59], 0, v[56:57]
	s_waitcnt lgkmcnt(0)
	v_lshlrev_b32_e32 v2, 16, v26
	v_and_b32_e32 v3, 0xffff0000, v26
	v_lshlrev_b32_e32 v4, 16, v27
	v_and_b32_e32 v5, 0xffff0000, v27
	v_lshlrev_b32_e32 v14, 16, v28
	v_and_b32_e32 v15, 0xffff0000, v28
	v_lshlrev_b32_e32 v16, 16, v29
	v_and_b32_e32 v17, 0xffff0000, v29
	v_add_u32_e32 v63, 0x210, v63
	ds_read2_b64 v[26:29], v63 offset1:32
	v_pk_fma_f32 v[30:31], v[146:147], v[22:23], v[158:159]
	v_pk_fma_f32 v[32:33], v[148:149], v[24:25], v[160:161]
	v_pk_fma_f32 v[34:35], v[134:135], v[10:11], v[154:155]
	v_pk_fma_f32 v[36:37], v[136:137], v[12:13], v[156:157]
	v_pk_fma_f32 v[30:31], v[142:143], v[18:19], v[30:31]
	v_pk_fma_f32 v[32:33], v[144:145], v[20:21], v[32:33]
	v_pk_fma_f32 v[34:35], v[130:131], v[6:7], v[34:35]
	v_pk_fma_f32 v[36:37], v[132:133], v[8:9], v[36:37]
	v_pk_fma_f32 v[30:31], v[150:151], v[14:15], v[30:31]
	v_pk_fma_f32 v[32:33], v[152:153], v[16:17], v[32:33]
	v_pk_fma_f32 v[34:35], v[138:139], v[2:3], v[34:35]
	v_pk_fma_f32 v[36:37], v[140:141], v[4:5], v[36:37]
	v_mul_f32_e32 v42, 0xbfb8aa3b, v30
	v_mul_f32_e32 v43, 0xbfb8aa3b, v31
	v_mul_f32_e32 v44, 0xbfb8aa3b, v32
	v_mul_f32_e32 v45, 0xbfb8aa3b, v33
	v_exp_f32_e32 v42, v42
	v_exp_f32_e32 v43, v43
	v_exp_f32_e32 v44, v44
	v_exp_f32_e32 v45, v45
	v_pk_add_f32 v[42:43], v[42:43], 1.0 op_sel_hi:[1,0]
	v_pk_add_f32 v[44:45], v[44:45], 1.0 op_sel_hi:[1,0]
	v_rcp_f32_e32 v46, v42
	v_rcp_f32_e32 v47, v43
	v_rcp_f32_e32 v48, v44
	v_rcp_f32_e32 v49, v45
	v_mul_f32_e32 v46, v30, v46
	v_mul_f32_e32 v47, v31, v47
	v_mul_f32_e32 v48, v32, v48
	v_mul_f32_e32 v49, v33, v49
	v_pk_mul_f32 v[34:35], v[34:35], v[46:47]
	v_pk_mul_f32 v[36:37], v[36:37], v[48:49]
	v_cvt_pk_bf16_f32 v66, v34, v35
	v_cvt_pk_bf16_f32 v67, v36, v37
	global_store_dwordx2 v[58:59], v[66:67], off
	v_lshl_add_u64 v[58:59], v[58:59], 0, v[56:57]
	s_waitcnt lgkmcnt(0)
	v_lshlrev_b32_e32 v6, 16, v26
	v_and_b32_e32 v7, 0xffff0000, v26
	v_lshlrev_b32_e32 v8, 16, v27
	v_and_b32_e32 v9, 0xffff0000, v27
	v_lshlrev_b32_e32 v18, 16, v28
	v_and_b32_e32 v19, 0xffff0000, v28
	v_lshlrev_b32_e32 v20, 16, v29
	v_and_b32_e32 v21, 0xffff0000, v29
	v_add_u32_e32 v63, 0x210, v63
	ds_read2_b64 v[26:29], v63 offset1:32
	v_pk_fma_f32 v[30:31], v[146:147], v[14:15], v[158:159]
	v_pk_fma_f32 v[32:33], v[148:149], v[16:17], v[160:161]
	v_pk_fma_f32 v[34:35], v[134:135], v[2:3], v[154:155]
	v_pk_fma_f32 v[36:37], v[136:137], v[4:5], v[156:157]
	v_pk_fma_f32 v[30:31], v[142:143], v[22:23], v[30:31]
	v_pk_fma_f32 v[32:33], v[144:145], v[24:25], v[32:33]
	v_pk_fma_f32 v[34:35], v[130:131], v[10:11], v[34:35]
	v_pk_fma_f32 v[36:37], v[132:133], v[12:13], v[36:37]
	v_pk_fma_f32 v[30:31], v[150:151], v[18:19], v[30:31]
	v_pk_fma_f32 v[32:33], v[152:153], v[20:21], v[32:33]
	v_pk_fma_f32 v[34:35], v[138:139], v[6:7], v[34:35]
	v_pk_fma_f32 v[36:37], v[140:141], v[8:9], v[36:37]
	v_mul_f32_e32 v42, 0xbfb8aa3b, v30
	v_mul_f32_e32 v43, 0xbfb8aa3b, v31
	v_mul_f32_e32 v44, 0xbfb8aa3b, v32
	v_mul_f32_e32 v45, 0xbfb8aa3b, v33
	v_exp_f32_e32 v42, v42
	v_exp_f32_e32 v43, v43
	v_exp_f32_e32 v44, v44
	v_exp_f32_e32 v45, v45
	v_pk_add_f32 v[42:43], v[42:43], 1.0 op_sel_hi:[1,0]
	v_pk_add_f32 v[44:45], v[44:45], 1.0 op_sel_hi:[1,0]
	v_rcp_f32_e32 v46, v42
	v_rcp_f32_e32 v47, v43
	v_rcp_f32_e32 v48, v44
	v_rcp_f32_e32 v49, v45
	v_mul_f32_e32 v46, v30, v46
	v_mul_f32_e32 v47, v31, v47
	v_mul_f32_e32 v48, v32, v48
	v_mul_f32_e32 v49, v33, v49
	v_pk_mul_f32 v[34:35], v[34:35], v[46:47]
	v_pk_mul_f32 v[36:37], v[36:37], v[48:49]
	v_cvt_pk_bf16_f32 v66, v34, v35
	v_cvt_pk_bf16_f32 v67, v36, v37
	global_store_dwordx2 v[58:59], v[66:67], off
	v_lshl_add_u64 v[58:59], v[58:59], 0, v[56:57]
	s_waitcnt lgkmcnt(0)
	v_lshlrev_b32_e32 v10, 16, v26
	v_and_b32_e32 v11, 0xffff0000, v26
	v_lshlrev_b32_e32 v12, 16, v27
	v_and_b32_e32 v13, 0xffff0000, v27
	v_lshlrev_b32_e32 v22, 16, v28
	v_and_b32_e32 v23, 0xffff0000, v28
	v_lshlrev_b32_e32 v24, 16, v29
	v_and_b32_e32 v25, 0xffff0000, v29
	v_add_u32_e32 v63, 0x210, v63
	ds_read2_b64 v[26:29], v63 offset1:32
	v_pk_fma_f32 v[30:31], v[146:147], v[18:19], v[158:159]
	v_pk_fma_f32 v[32:33], v[148:149], v[20:21], v[160:161]
	v_pk_fma_f32 v[34:35], v[134:135], v[6:7], v[154:155]
	v_pk_fma_f32 v[36:37], v[136:137], v[8:9], v[156:157]
	v_pk_fma_f32 v[30:31], v[142:143], v[14:15], v[30:31]
	v_pk_fma_f32 v[32:33], v[144:145], v[16:17], v[32:33]
	v_pk_fma_f32 v[34:35], v[130:131], v[2:3], v[34:35]
	v_pk_fma_f32 v[36:37], v[132:133], v[4:5], v[36:37]
	v_pk_fma_f32 v[30:31], v[150:151], v[22:23], v[30:31]
	v_pk_fma_f32 v[32:33], v[152:153], v[24:25], v[32:33]
	v_pk_fma_f32 v[34:35], v[138:139], v[10:11], v[34:35]
	v_pk_fma_f32 v[36:37], v[140:141], v[12:13], v[36:37]
	v_mul_f32_e32 v42, 0xbfb8aa3b, v30
	v_mul_f32_e32 v43, 0xbfb8aa3b, v31
	v_mul_f32_e32 v44, 0xbfb8aa3b, v32
	v_mul_f32_e32 v45, 0xbfb8aa3b, v33
	v_exp_f32_e32 v42, v42
	v_exp_f32_e32 v43, v43
	v_exp_f32_e32 v44, v44
	v_exp_f32_e32 v45, v45
	v_pk_add_f32 v[42:43], v[42:43], 1.0 op_sel_hi:[1,0]
	v_pk_add_f32 v[44:45], v[44:45], 1.0 op_sel_hi:[1,0]
	v_rcp_f32_e32 v46, v42
	v_rcp_f32_e32 v47, v43
	v_rcp_f32_e32 v48, v44
	v_rcp_f32_e32 v49, v45
	v_mul_f32_e32 v46, v30, v46
	v_mul_f32_e32 v47, v31, v47
	v_mul_f32_e32 v48, v32, v48
	v_mul_f32_e32 v49, v33, v49
	v_pk_mul_f32 v[34:35], v[34:35], v[46:47]
	v_pk_mul_f32 v[36:37], v[36:37], v[48:49]
	v_cvt_pk_bf16_f32 v66, v34, v35
	v_cvt_pk_bf16_f32 v67, v36, v37
	global_store_dwordx2 v[58:59], v[66:67], off
	v_lshl_add_u64 v[58:59], v[58:59], 0, v[56:57]
	s_waitcnt lgkmcnt(0)
	v_lshlrev_b32_e32 v2, 16, v26
	v_and_b32_e32 v3, 0xffff0000, v26
	v_lshlrev_b32_e32 v4, 16, v27
	v_and_b32_e32 v5, 0xffff0000, v27
	v_lshlrev_b32_e32 v14, 16, v28
	v_and_b32_e32 v15, 0xffff0000, v28
	v_lshlrev_b32_e32 v16, 16, v29
	v_and_b32_e32 v17, 0xffff0000, v29
	v_add_u32_e32 v63, 0x210, v63
	ds_read2_b64 v[26:29], v63 offset1:32
	v_pk_fma_f32 v[30:31], v[146:147], v[22:23], v[158:159]
	v_pk_fma_f32 v[32:33], v[148:149], v[24:25], v[160:161]
	v_pk_fma_f32 v[34:35], v[134:135], v[10:11], v[154:155]
	v_pk_fma_f32 v[36:37], v[136:137], v[12:13], v[156:157]
	v_pk_fma_f32 v[30:31], v[142:143], v[18:19], v[30:31]
	v_pk_fma_f32 v[32:33], v[144:145], v[20:21], v[32:33]
	v_pk_fma_f32 v[34:35], v[130:131], v[6:7], v[34:35]
	v_pk_fma_f32 v[36:37], v[132:133], v[8:9], v[36:37]
	v_pk_fma_f32 v[30:31], v[150:151], v[14:15], v[30:31]
	v_pk_fma_f32 v[32:33], v[152:153], v[16:17], v[32:33]
	v_pk_fma_f32 v[34:35], v[138:139], v[2:3], v[34:35]
	v_pk_fma_f32 v[36:37], v[140:141], v[4:5], v[36:37]
	v_mul_f32_e32 v42, 0xbfb8aa3b, v30
	v_mul_f32_e32 v43, 0xbfb8aa3b, v31
	v_mul_f32_e32 v44, 0xbfb8aa3b, v32
	v_mul_f32_e32 v45, 0xbfb8aa3b, v33
	v_exp_f32_e32 v42, v42
	v_exp_f32_e32 v43, v43
	v_exp_f32_e32 v44, v44
	v_exp_f32_e32 v45, v45
	v_pk_add_f32 v[42:43], v[42:43], 1.0 op_sel_hi:[1,0]
	v_pk_add_f32 v[44:45], v[44:45], 1.0 op_sel_hi:[1,0]
	v_rcp_f32_e32 v46, v42
	v_rcp_f32_e32 v47, v43
	v_rcp_f32_e32 v48, v44
	v_rcp_f32_e32 v49, v45
	v_mul_f32_e32 v46, v30, v46
	v_mul_f32_e32 v47, v31, v47
	v_mul_f32_e32 v48, v32, v48
	v_mul_f32_e32 v49, v33, v49
	v_pk_mul_f32 v[34:35], v[34:35], v[46:47]
	v_pk_mul_f32 v[36:37], v[36:37], v[48:49]
	v_cvt_pk_bf16_f32 v66, v34, v35
	v_cvt_pk_bf16_f32 v67, v36, v37
	global_store_dwordx2 v[58:59], v[66:67], off
	v_lshl_add_u64 v[58:59], v[58:59], 0, v[56:57]
	s_waitcnt lgkmcnt(0)
	v_lshlrev_b32_e32 v6, 16, v26
	v_and_b32_e32 v7, 0xffff0000, v26
	v_lshlrev_b32_e32 v8, 16, v27
	v_and_b32_e32 v9, 0xffff0000, v27
	v_lshlrev_b32_e32 v18, 16, v28
	v_and_b32_e32 v19, 0xffff0000, v28
	v_lshlrev_b32_e32 v20, 16, v29
	v_and_b32_e32 v21, 0xffff0000, v29
	v_add_u32_e32 v63, 0x210, v63
	ds_read2_b64 v[26:29], v63 offset1:32
	v_pk_fma_f32 v[30:31], v[146:147], v[14:15], v[158:159]
	v_pk_fma_f32 v[32:33], v[148:149], v[16:17], v[160:161]
	v_pk_fma_f32 v[34:35], v[134:135], v[2:3], v[154:155]
	v_pk_fma_f32 v[36:37], v[136:137], v[4:5], v[156:157]
	v_pk_fma_f32 v[30:31], v[142:143], v[22:23], v[30:31]
	v_pk_fma_f32 v[32:33], v[144:145], v[24:25], v[32:33]
	v_pk_fma_f32 v[34:35], v[130:131], v[10:11], v[34:35]
	v_pk_fma_f32 v[36:37], v[132:133], v[12:13], v[36:37]
	v_pk_fma_f32 v[30:31], v[150:151], v[18:19], v[30:31]
	v_pk_fma_f32 v[32:33], v[152:153], v[20:21], v[32:33]
	v_pk_fma_f32 v[34:35], v[138:139], v[6:7], v[34:35]
	v_pk_fma_f32 v[36:37], v[140:141], v[8:9], v[36:37]
	v_mul_f32_e32 v42, 0xbfb8aa3b, v30
	v_mul_f32_e32 v43, 0xbfb8aa3b, v31
	v_mul_f32_e32 v44, 0xbfb8aa3b, v32
	v_mul_f32_e32 v45, 0xbfb8aa3b, v33
	v_exp_f32_e32 v42, v42
	v_exp_f32_e32 v43, v43
	v_exp_f32_e32 v44, v44
	v_exp_f32_e32 v45, v45
	v_pk_add_f32 v[42:43], v[42:43], 1.0 op_sel_hi:[1,0]
	v_pk_add_f32 v[44:45], v[44:45], 1.0 op_sel_hi:[1,0]
	v_rcp_f32_e32 v46, v42
	v_rcp_f32_e32 v47, v43
	v_rcp_f32_e32 v48, v44
	v_rcp_f32_e32 v49, v45
	v_mul_f32_e32 v46, v30, v46
	v_mul_f32_e32 v47, v31, v47
	v_mul_f32_e32 v48, v32, v48
	v_mul_f32_e32 v49, v33, v49
	v_pk_mul_f32 v[34:35], v[34:35], v[46:47]
	v_pk_mul_f32 v[36:37], v[36:37], v[48:49]
	v_cvt_pk_bf16_f32 v66, v34, v35
	v_cvt_pk_bf16_f32 v67, v36, v37
	global_store_dwordx2 v[58:59], v[66:67], off
	v_lshl_add_u64 v[58:59], v[58:59], 0, v[56:57]
	s_waitcnt lgkmcnt(0)
	v_lshlrev_b32_e32 v10, 16, v26
	v_and_b32_e32 v11, 0xffff0000, v26
	v_lshlrev_b32_e32 v12, 16, v27
	v_and_b32_e32 v13, 0xffff0000, v27
	v_lshlrev_b32_e32 v22, 16, v28
	v_and_b32_e32 v23, 0xffff0000, v28
	v_lshlrev_b32_e32 v24, 16, v29
	v_and_b32_e32 v25, 0xffff0000, v29
	v_add_u32_e32 v63, 0x210, v63
	ds_read2_b64 v[26:29], v63 offset1:32
	v_pk_fma_f32 v[30:31], v[146:147], v[18:19], v[158:159]
	v_pk_fma_f32 v[32:33], v[148:149], v[20:21], v[160:161]
	v_pk_fma_f32 v[34:35], v[134:135], v[6:7], v[154:155]
	v_pk_fma_f32 v[36:37], v[136:137], v[8:9], v[156:157]
	v_pk_fma_f32 v[30:31], v[142:143], v[14:15], v[30:31]
	v_pk_fma_f32 v[32:33], v[144:145], v[16:17], v[32:33]
	v_pk_fma_f32 v[34:35], v[130:131], v[2:3], v[34:35]
	v_pk_fma_f32 v[36:37], v[132:133], v[4:5], v[36:37]
	v_pk_fma_f32 v[30:31], v[150:151], v[22:23], v[30:31]
	v_pk_fma_f32 v[32:33], v[152:153], v[24:25], v[32:33]
	v_pk_fma_f32 v[34:35], v[138:139], v[10:11], v[34:35]
	v_pk_fma_f32 v[36:37], v[140:141], v[12:13], v[36:37]
	v_mul_f32_e32 v42, 0xbfb8aa3b, v30
	v_mul_f32_e32 v43, 0xbfb8aa3b, v31
	v_mul_f32_e32 v44, 0xbfb8aa3b, v32
	v_mul_f32_e32 v45, 0xbfb8aa3b, v33
	v_exp_f32_e32 v42, v42
	v_exp_f32_e32 v43, v43
	v_exp_f32_e32 v44, v44
	v_exp_f32_e32 v45, v45
	v_pk_add_f32 v[42:43], v[42:43], 1.0 op_sel_hi:[1,0]
	v_pk_add_f32 v[44:45], v[44:45], 1.0 op_sel_hi:[1,0]
	v_rcp_f32_e32 v46, v42
	v_rcp_f32_e32 v47, v43
	v_rcp_f32_e32 v48, v44
	v_rcp_f32_e32 v49, v45
	v_mul_f32_e32 v46, v30, v46
	v_mul_f32_e32 v47, v31, v47
	v_mul_f32_e32 v48, v32, v48
	v_mul_f32_e32 v49, v33, v49
	v_pk_mul_f32 v[34:35], v[34:35], v[46:47]
	v_pk_mul_f32 v[36:37], v[36:37], v[48:49]
	v_cvt_pk_bf16_f32 v66, v34, v35
	v_cvt_pk_bf16_f32 v67, v36, v37
	global_store_dwordx2 v[58:59], v[66:67], off
	v_lshl_add_u64 v[58:59], v[58:59], 0, v[56:57]
	s_waitcnt lgkmcnt(0)
	v_lshlrev_b32_e32 v2, 16, v26
	v_and_b32_e32 v3, 0xffff0000, v26
	v_lshlrev_b32_e32 v4, 16, v27
	v_and_b32_e32 v5, 0xffff0000, v27
	v_lshlrev_b32_e32 v14, 16, v28
	v_and_b32_e32 v15, 0xffff0000, v28
	v_lshlrev_b32_e32 v16, 16, v29
	v_and_b32_e32 v17, 0xffff0000, v29
	v_add_u32_e32 v63, 0x210, v63
	ds_read2_b64 v[26:29], v63 offset1:32
	v_pk_fma_f32 v[30:31], v[146:147], v[22:23], v[158:159]
	v_pk_fma_f32 v[32:33], v[148:149], v[24:25], v[160:161]
	v_pk_fma_f32 v[34:35], v[134:135], v[10:11], v[154:155]
	v_pk_fma_f32 v[36:37], v[136:137], v[12:13], v[156:157]
	v_pk_fma_f32 v[30:31], v[142:143], v[18:19], v[30:31]
	v_pk_fma_f32 v[32:33], v[144:145], v[20:21], v[32:33]
	v_pk_fma_f32 v[34:35], v[130:131], v[6:7], v[34:35]
	v_pk_fma_f32 v[36:37], v[132:133], v[8:9], v[36:37]
	v_pk_fma_f32 v[30:31], v[150:151], v[14:15], v[30:31]
	v_pk_fma_f32 v[32:33], v[152:153], v[16:17], v[32:33]
	v_pk_fma_f32 v[34:35], v[138:139], v[2:3], v[34:35]
	v_pk_fma_f32 v[36:37], v[140:141], v[4:5], v[36:37]
	v_mul_f32_e32 v42, 0xbfb8aa3b, v30
	v_mul_f32_e32 v43, 0xbfb8aa3b, v31
	v_mul_f32_e32 v44, 0xbfb8aa3b, v32
	v_mul_f32_e32 v45, 0xbfb8aa3b, v33
	v_exp_f32_e32 v42, v42
	v_exp_f32_e32 v43, v43
	v_exp_f32_e32 v44, v44
	v_exp_f32_e32 v45, v45
	v_pk_add_f32 v[42:43], v[42:43], 1.0 op_sel_hi:[1,0]
	v_pk_add_f32 v[44:45], v[44:45], 1.0 op_sel_hi:[1,0]
	v_rcp_f32_e32 v46, v42
	v_rcp_f32_e32 v47, v43
	v_rcp_f32_e32 v48, v44
	v_rcp_f32_e32 v49, v45
	v_mul_f32_e32 v46, v30, v46
	v_mul_f32_e32 v47, v31, v47
	v_mul_f32_e32 v48, v32, v48
	v_mul_f32_e32 v49, v33, v49
	v_pk_mul_f32 v[34:35], v[34:35], v[46:47]
	v_pk_mul_f32 v[36:37], v[36:37], v[48:49]
	v_cvt_pk_bf16_f32 v66, v34, v35
	v_cvt_pk_bf16_f32 v67, v36, v37
	global_store_dwordx2 v[58:59], v[66:67], off
	v_lshl_add_u64 v[58:59], v[58:59], 0, v[56:57]
	s_waitcnt lgkmcnt(0)
	v_lshlrev_b32_e32 v6, 16, v26
	v_and_b32_e32 v7, 0xffff0000, v26
	v_lshlrev_b32_e32 v8, 16, v27
	v_and_b32_e32 v9, 0xffff0000, v27
	v_lshlrev_b32_e32 v18, 16, v28
	v_and_b32_e32 v19, 0xffff0000, v28
	v_lshlrev_b32_e32 v20, 16, v29
	v_and_b32_e32 v21, 0xffff0000, v29
	v_add_u32_e32 v63, 0x210, v63
	ds_read2_b64 v[26:29], v63 offset1:32
	v_pk_fma_f32 v[30:31], v[146:147], v[14:15], v[158:159]
	v_pk_fma_f32 v[32:33], v[148:149], v[16:17], v[160:161]
	v_pk_fma_f32 v[34:35], v[134:135], v[2:3], v[154:155]
	v_pk_fma_f32 v[36:37], v[136:137], v[4:5], v[156:157]
	v_pk_fma_f32 v[30:31], v[142:143], v[22:23], v[30:31]
	v_pk_fma_f32 v[32:33], v[144:145], v[24:25], v[32:33]
	v_pk_fma_f32 v[34:35], v[130:131], v[10:11], v[34:35]
	v_pk_fma_f32 v[36:37], v[132:133], v[12:13], v[36:37]
	v_pk_fma_f32 v[30:31], v[150:151], v[18:19], v[30:31]
	v_pk_fma_f32 v[32:33], v[152:153], v[20:21], v[32:33]
	v_pk_fma_f32 v[34:35], v[138:139], v[6:7], v[34:35]
	v_pk_fma_f32 v[36:37], v[140:141], v[8:9], v[36:37]
	v_mul_f32_e32 v42, 0xbfb8aa3b, v30
	v_mul_f32_e32 v43, 0xbfb8aa3b, v31
	v_mul_f32_e32 v44, 0xbfb8aa3b, v32
	v_mul_f32_e32 v45, 0xbfb8aa3b, v33
	v_exp_f32_e32 v42, v42
	v_exp_f32_e32 v43, v43
	v_exp_f32_e32 v44, v44
	v_exp_f32_e32 v45, v45
	v_pk_add_f32 v[42:43], v[42:43], 1.0 op_sel_hi:[1,0]
	v_pk_add_f32 v[44:45], v[44:45], 1.0 op_sel_hi:[1,0]
	v_rcp_f32_e32 v46, v42
	v_rcp_f32_e32 v47, v43
	v_rcp_f32_e32 v48, v44
	v_rcp_f32_e32 v49, v45
	v_mul_f32_e32 v46, v30, v46
	v_mul_f32_e32 v47, v31, v47
	v_mul_f32_e32 v48, v32, v48
	v_mul_f32_e32 v49, v33, v49
	v_pk_mul_f32 v[34:35], v[34:35], v[46:47]
	v_pk_mul_f32 v[36:37], v[36:37], v[48:49]
	v_cvt_pk_bf16_f32 v66, v34, v35
	v_cvt_pk_bf16_f32 v67, v36, v37
	s_and_saveexec_b64 s[4:5], vcc
	global_store_dwordx2 v[58:59], v[66:67], off
	s_or_b64 exec, exec, s[4:5]
	v_lshl_add_u64 v[58:59], v[58:59], 0, v[56:57]
	s_waitcnt lgkmcnt(0)
	v_lshlrev_b32_e32 v10, 16, v26
	v_and_b32_e32 v11, 0xffff0000, v26
	v_lshlrev_b32_e32 v12, 16, v27
	v_and_b32_e32 v13, 0xffff0000, v27
	v_lshlrev_b32_e32 v22, 16, v28
	v_and_b32_e32 v23, 0xffff0000, v28
	v_lshlrev_b32_e32 v24, 16, v29
	v_and_b32_e32 v25, 0xffff0000, v29
	v_pk_fma_f32 v[30:31], v[146:147], v[18:19], v[158:159]
	v_pk_fma_f32 v[32:33], v[148:149], v[20:21], v[160:161]
	v_pk_fma_f32 v[34:35], v[134:135], v[6:7], v[154:155]
	v_pk_fma_f32 v[36:37], v[136:137], v[8:9], v[156:157]
	v_pk_fma_f32 v[30:31], v[142:143], v[14:15], v[30:31]
	v_pk_fma_f32 v[32:33], v[144:145], v[16:17], v[32:33]
	v_pk_fma_f32 v[34:35], v[130:131], v[2:3], v[34:35]
	v_pk_fma_f32 v[36:37], v[132:133], v[4:5], v[36:37]
	v_pk_fma_f32 v[30:31], v[150:151], v[22:23], v[30:31]
	v_pk_fma_f32 v[32:33], v[152:153], v[24:25], v[32:33]
	v_pk_fma_f32 v[34:35], v[138:139], v[10:11], v[34:35]
	v_pk_fma_f32 v[36:37], v[140:141], v[12:13], v[36:37]
	v_mul_f32_e32 v42, 0xbfb8aa3b, v30
	v_mul_f32_e32 v43, 0xbfb8aa3b, v31
	v_mul_f32_e32 v44, 0xbfb8aa3b, v32
	v_mul_f32_e32 v45, 0xbfb8aa3b, v33
	v_exp_f32_e32 v42, v42
	v_exp_f32_e32 v43, v43
	v_exp_f32_e32 v44, v44
	v_exp_f32_e32 v45, v45
	v_pk_add_f32 v[42:43], v[42:43], 1.0 op_sel_hi:[1,0]
	v_pk_add_f32 v[44:45], v[44:45], 1.0 op_sel_hi:[1,0]
	v_rcp_f32_e32 v46, v42
	v_rcp_f32_e32 v47, v43
	v_rcp_f32_e32 v48, v44
	v_rcp_f32_e32 v49, v45
	v_mul_f32_e32 v46, v30, v46
	v_mul_f32_e32 v47, v31, v47
	v_mul_f32_e32 v48, v32, v48
	v_mul_f32_e32 v49, v33, v49
	v_pk_mul_f32 v[34:35], v[34:35], v[46:47]
	v_pk_mul_f32 v[36:37], v[36:37], v[48:49]
	v_cvt_pk_bf16_f32 v66, v34, v35
	v_cvt_pk_bf16_f32 v67, v36, v37
	s_and_saveexec_b64 s[4:5], vcc
	global_store_dwordx2 v[58:59], v[66:67], off
	s_or_b64 exec, exec, s[4:5]
	v_lshl_add_u64 v[58:59], v[58:59], 0, v[56:57]
	s_branch .Lconv_done
